# attention tile loop: the per-tile workgroup barrier moved from the top of the odd iteration to behind PV MFMA 4 (those MFMAs need nothing the barrier guards), K reads and LDS-DMA set-up follow it, DMA
# baseline (speedup 1.0000x reference)
; __device__ __forceinline__ void diff_unit_lds(LAS unsigned char* lds, const bf16* Qd, const bf16* Kd, const bf16* VdT, bf16* MIX, const float* ghead, float lam, int head, int u, int wave, int lane) {
;     ...
;         if ((T & 1) == 0) {
;             asm volatile("s_waitcnt vmcnt(0) lgkmcnt(0)\n\ts_barrier" ::: "memory");
;             if (T + 2 < nT) DIFF_ISSUE(T + 2);
;             if (T + 3 < nT) DIFF_ISSUE(T + 3);
;         }
;         if (T <= Tlast) {
;             const bool part = (T == Tlast);
;             const bool masked = part && (h == 1);
;             f32x16 S0 = NEGM, S1 = NEGM;
; #pragma unroll
;             for (int ds = 0; ds < 4; ++ds) S0 = MFMA32(*(const LAS bf16x8*)(st + koff + (((2 * ds + h) ^ kx) << 4)), qf[ds], S0);
;             if (!part) {
; #pragma unroll
;                 for (int ds = 0; ds < 4; ++ds) S1 = MFMA32(*(const LAS bf16x8*)(st + koff + 4096 + (((2 * ds + h) ^ kx) << 4)), qf[ds], S1);
;             }
;             float tmax = S0[0];
; #pragma unroll
;             for (int i = 1; i < 16; ++i) tmax = fmaxf(tmax, S0[i]);
;             if (masked) tmax = -1e30f;
;             if (!part) {
; #pragma unroll
;                 for (int i = 0; i < 16; ++i) tmax = fmaxf(tmax, S1[i]);
;             }
;             tmax = fmaxf(tmax, xhalf(tmax, h));
;             if (T == 0 || __any(tmax > 8.0f)) {
;                 const float delta = (T == 0) ? tmax : fmaxf(tmax, 0.f), alpha = (T == 0) ? 1.0f : __builtin_amdgcn_exp2f(-delta);
;                 l *= alpha;
; #pragma unroll
;                 for (int b = 0; b < 4; ++b)
; #pragma unroll
;                     for (int i = 0; i < 16; ++i) O[b][i] *= alpha;
;                 m_used += delta;
; #pragma unroll
;                 for (int i = 0; i < 16; ++i) { NEGM[i] = -m_used; S0[i] -= delta; S1[i] -= delta; }
;             }
;             {
;                 float p[16]; float ps = 0.f;
; #pragma unroll
;                 for (int i = 0; i < 16; ++i) { p[i] = __builtin_amdgcn_exp2f(S0[i]); ps += p[i]; }
;                 if (masked) {
; #pragma unroll
;                     for (int i = 0; i < 16; ++i) p[i] = 0.f;
;                     ps = 0.f;
;                 }
;                 l += ps;
;                 const bf16x8 pk0 = pack8(p[0], p[1], p[2], p[3], p[4], p[5], p[6], p[7]);
;                 const bf16x8 pk1 = pack8(p[8], p[9], p[10], p[11], p[12], p[13], p[14], p[15]);
.Lq_rlc_e:
	s_waitcnt lgkmcnt(8)
	v_mfma_f32_32x32x16_bf16 v[82:97], v[164:167], v[126:129], v[66:81]
	v_exp_f32_e32 v109, v109
	v_add_f32_e32 v251, v251, v107
	v_exp_f32_e32 v110, v110
	v_add_f32_e32 v251, v251, v108
	v_mfma_f32_32x32x16_bf16 v[82:97], v[168:171], v[122:125], v[82:97]
	v_exp_f32_e32 v111, v111
	v_add_f32_e32 v251, v251, v109
	v_exp_f32_e32 v112, v112
	v_add_f32_e32 v251, v251, v110
	v_mfma_f32_32x32x16_bf16 v[82:97], v[172:175], v[118:121], v[82:97]
	v_exp_f32_e32 v113, v113
	v_add_f32_e32 v251, v251, v111
	v_cvt_pk_bf16_f32 v102, v106, v107
	v_add_f32_e32 v251, v251, v112
	v_mfma_f32_32x32x16_bf16 v[82:97], v[176:179], v[114:117], v[82:97]
	v_cvt_pk_bf16_f32 v103, v108, v109
	v_cvt_pk_bf16_f32 v104, v110, v111
	v_cvt_pk_bf16_f32 v105, v112, v113
	v_add_f32_e32 v251, v251, v113
	v_add_f32_e32 v218, v218, v251
	s_add_i32 s94, s94, 1
	s_add_i32 s0, s94, 1
	s_lshr_b32 s57, s0, 1
	s_cmp_lt_u32 s57, 2
	s_cbranch_scc1 .Lq_odd_nodma
	s_cmp_gt_u32 s57, s93
	s_cbranch_scc1 .Lq_odd_nodma
	s_lshr_b32 s0, s94, 1
	s_and_b32 s0, s0, 3
	s_lshl_b32 s95, s0, 15
	s_and_b32 s0, s57, 3
	s_lshl_b32 s58, s0, 15
	v_add_u32_e32 v208, s95, v206
	v_add_u32_e32 v213, s95, v207
	s_waitcnt lgkmcnt(0)
	v_mfma_f32_32x32x16_bf16 v[50:65], v[220:223], v[98:101], v[50:65]
	ds_read_b128 v[220:223], v208 offset:16384
	v_max3_f32 v1, v82, v83, v84
	v_max3_f32 v1, v1, v85, v86
	v_max3_f32 v1, v1, v87, v88
	v_max3_f32 v1, v1, v89, v90
	v_max3_f32 v1, v1, v91, v92
	v_mfma_f32_32x32x16_bf16 v[34:49], v[226:229], v[98:101], v[34:49]
	ds_read_b128 v[226:229], v208 offset:20480
	v_max3_f32 v1, v1, v93, v94
	v_max3_f32 v1, v1, v95, v96
	v_max_f32_e32 v224, v1, v97
	v_max_f32_e32 v225, v1, v97
	v_mfma_f32_32x32x16_bf16 v[18:33], v[230:233], v[98:101], v[18:33]
	ds_read_b128 v[230:233], v208 offset:24576
	s_nop 1
	v_permlane32_swap_b32_e32 v224, v225
	v_max_f32_e32 v1, v224, v225
	v_cmp_lt_f32_e32 vcc, s96, v1
	s_cbranch_vccnz .Lq_re_od
.Lq_rec_od:
	v_mfma_f32_32x32x16_bf16 v[2:17], v[234:237], v[98:101], v[2:17]
	ds_read_b128 v[234:237], v208 offset:28672
	v_exp_f32_e32 v82, v82
	v_exp_f32_e32 v83, v83
	v_exp_f32_e32 v84, v84
	v_add_f32_e32 v251, v82, v83
	v_exp_f32_e32 v85, v85
	s_add_i32 s1, s93, 1
	s_cmp_le_u32 s57, s1
	s_cbranch_scc1 .Lq_w4_od
	s_waitcnt vmcnt(0)
	s_branch .Lq_wd_od

; __device__ __forceinline__ void diff_unit_lds(LAS unsigned char* lds, const bf16* Qd, const bf16* Kd, const bf16* VdT, bf16* MIX, const float* ghead, float lam, int head, int u, int wave, int lane) {
;     ...
;         if ((T & 1) == 0) {
;             asm volatile("s_waitcnt vmcnt(0) lgkmcnt(0)\n\ts_barrier" ::: "memory");
;             if (T + 2 < nT) DIFF_ISSUE(T + 2);
;             if (T + 3 < nT) DIFF_ISSUE(T + 3);
;         }
;         if (T <= Tlast) {
;             const bool part = (T == Tlast);
;             const bool masked = part && (h == 1);
;             f32x16 S0 = NEGM, S1 = NEGM;
; #pragma unroll
;             for (int ds = 0; ds < 4; ++ds) S0 = MFMA32(*(const LAS bf16x8*)(st + koff + (((2 * ds + h) ^ kx) << 4)), qf[ds], S0);
;             if (!part) {
; #pragma unroll
;                 for (int ds = 0; ds < 4; ++ds) S1 = MFMA32(*(const LAS bf16x8*)(st + koff + 4096 + (((2 * ds + h) ^ kx) << 4)), qf[ds], S1);
;             }
;             float tmax = S0[0];
; #pragma unroll
;             for (int i = 1; i < 16; ++i) tmax = fmaxf(tmax, S0[i]);
;             if (masked) tmax = -1e30f;
;             if (!part) {
; #pragma unroll
;                 for (int i = 0; i < 16; ++i) tmax = fmaxf(tmax, S1[i]);
;             }
;             tmax = fmaxf(tmax, xhalf(tmax, h));
;             if (T == 0 || __any(tmax > 8.0f)) {
;                 const float delta = (T == 0) ? tmax : fmaxf(tmax, 0.f), alpha = (T == 0) ? 1.0f : __builtin_amdgcn_exp2f(-delta);
;                 l *= alpha;
; #pragma unroll
;                 for (int b = 0; b < 4; ++b)
; #pragma unroll
;                     for (int i = 0; i < 16; ++i) O[b][i] *= alpha;
;                 m_used += delta;
; #pragma unroll
;                 for (int i = 0; i < 16; ++i) { NEGM[i] = -m_used; S0[i] -= delta; S1[i] -= delta; }
;             }
;             {
;                 float p[16]; float ps = 0.f;
; #pragma unroll
;                 for (int i = 0; i < 16; ++i) { p[i] = __builtin_amdgcn_exp2f(S0[i]); ps += p[i]; }
;                 if (masked) {
; #pragma unroll
;                     for (int i = 0; i < 16; ++i) p[i] = 0.f;
;                     ps = 0.f;
;                 }
;                 l += ps;
;                 const bf16x8 pk0 = pack8(p[0], p[1], p[2], p[3], p[4], p[5], p[6], p[7]);
;                 const bf16x8 pk1 = pack8(p[8], p[9], p[10], p[11], p[12], p[13], p[14], p[15]);
.Lq_wd_od:
	s_barrier
	s_add_i32 s6, s57, 2
	s_and_b32 s0, s6, 3
	s_lshl_b32 s0, s0, 15
	s_add_i32 s1, s0, s33
	s_mov_b32 s7, m0
	v_add_u32_e32 v203, s58, v209
	ds_read_b128 v[164:167], v203
	v_add_u32_e32 v204, s58, v210
	ds_read_b128 v[168:171], v204
	v_add_u32_e32 v192, s58, v211
	ds_read_b128 v[172:175], v192
	v_add_u32_e32 v193, s58, v212
	ds_read_b128 v[176:179], v193
	v_mfma_f32_32x32x16_bf16 v[50:65], v[238:241], v[102:105], v[50:65]
	ds_read_b128 v[238:241], v213 offset:16384
	s_lshl_b32 s8, s6, 16
	s_mov_b32 s9, 0
	s_mov_b32 m0, s1
	v_lshl_add_u64 v[180:181], v[158:159], 0, s[8:9]
	global_load_lds_dwordx4 v[180:181], off
	v_exp_f32_e32 v86, v86
	v_add_f32_e32 v251, v251, v84
	v_exp_f32_e32 v87, v87
	v_add_f32_e32 v251, v251, v85
	v_exp_f32_e32 v88, v88
	v_mfma_f32_32x32x16_bf16 v[34:49], v[242:245], v[102:105], v[34:49]
	ds_read_b128 v[242:245], v213 offset:20480
	s_add_i32 s8, s8, 0x80
	s_add_i32 s0, s1, 0x2000
	s_mov_b32 m0, s0
	v_lshl_add_u64 v[182:183], v[158:159], 0, s[8:9]
	global_load_lds_dwordx4 v[182:183], off
	v_add_f32_e32 v251, v251, v86
	v_exp_f32_e32 v89, v89
	v_add_f32_e32 v251, v251, v87
	v_cvt_pk_bf16_f32 v82, v82, v83
	v_add_f32_e32 v251, v251, v88
	v_mfma_f32_32x32x16_bf16 v[18:33], v[246:249], v[102:105], v[18:33]
	ds_read_b128 v[246:249], v213 offset:24576
	s_lshl_b32 s8, s6, 7
	s_add_i32 s0, s1, 0x4000
	s_mov_b32 m0, s0
	v_lshl_add_u64 v[184:185], v[156:157], 0, s[8:9]
	global_load_lds_dwordx4 v[184:185], off
	v_cvt_pk_bf16_f32 v83, v84, v85
	v_cvt_pk_bf16_f32 v84, v86, v87
	v_cvt_pk_bf16_f32 v85, v88, v89
	v_add_f32_e32 v251, v251, v89
	v_mfma_f32_32x32x16_bf16 v[2:17], v[252:255], v[102:105], v[2:17]
	ds_read_b128 v[252:255], v213 offset:28672
	s_add_i32 s0, s1, 0x6000
	s_mov_b32 m0, s0
	v_lshl_add_u64 v[186:187], v[162:163], 0, s[8:9]
	global_load_lds_dwordx4 v[186:187], off
	s_mov_b32 m0, s7
	v_exp_f32_e32 v90, v90
	v_exp_f32_e32 v91, v91
	v_exp_f32_e32 v92, v92
	v_add_f32_e32 v251, v251, v90
	s_cmp_lg_u32 s59, 0
	s_cbranch_scc1 .Lq_rl_od
.Lq_rlc_od:
	s_waitcnt lgkmcnt(4)
	v_mfma_f32_32x32x16_bf16 v[98:113], v[164:167], v[126:129], v[66:81]
	v_exp_f32_e32 v93, v93
	v_add_f32_e32 v251, v251, v91
	v_exp_f32_e32 v94, v94
	v_add_f32_e32 v251, v251, v92
	v_mfma_f32_32x32x16_bf16 v[98:113], v[168:171], v[122:125], v[98:113]
	v_exp_f32_e32 v95, v95
	v_add_f32_e32 v251, v251, v93
	v_exp_f32_e32 v96, v96
	v_add_f32_e32 v251, v251, v94
	v_mfma_f32_32x32x16_bf16 v[98:113], v[172:175], v[118:121], v[98:113]
	v_exp_f32_e32 v97, v97
	v_add_f32_e32 v251, v251, v95
	v_cvt_pk_bf16_f32 v86, v90, v91
	v_add_f32_e32 v251, v251, v96
	v_mfma_f32_32x32x16_bf16 v[98:113], v[176:179], v[114:117], v[98:113]
	v_cvt_pk_bf16_f32 v87, v92, v93
	v_cvt_pk_bf16_f32 v88, v94, v95
	v_cvt_pk_bf16_f32 v89, v96, v97
	v_add_f32_e32 v251, v251, v97
	v_add_f32_e32 v218, v218, v251
	s_branch .Lq_odd_join
.Lq_odd_nodma:
	s_lshr_b32 s0, s94, 1
	s_and_b32 s0, s0, 3
	s_lshl_b32 s95, s0, 15
	s_and_b32 s0, s57, 3
	s_lshl_b32 s58, s0, 15
	v_add_u32_e32 v208, s95, v206
	v_add_u32_e32 v213, s95, v207
	s_waitcnt lgkmcnt(0)
	v_mfma_f32_32x32x16_bf16 v[50:65], v[220:223], v[98:101], v[50:65]
	ds_read_b128 v[220:223], v208 offset:16384
	v_max3_f32 v1, v82, v83, v84
	v_max3_f32 v1, v1, v85, v86
	v_max3_f32 v1, v1, v87, v88
	v_max3_f32 v1, v1, v89, v90
	v_max3_f32 v1, v1, v91, v92
	v_mfma_f32_32x32x16_bf16 v[34:49], v[226:229], v[98:101], v[34:49]
	ds_read_b128 v[226:229], v208 offset:20480
	v_max3_f32 v1, v1, v93, v94
	v_max3_f32 v1, v1, v95, v96
	v_max_f32_e32 v224, v1, v97
	v_max_f32_e32 v225, v1, v97
	v_mfma_f32_32x32x16_bf16 v[18:33], v[230:233], v[98:101], v[18:33]
	ds_read_b128 v[230:233], v208 offset:24576
	s_nop 1
	v_permlane32_swap_b32_e32 v224, v225
	v_max_f32_e32 v1, v224, v225
	v_cmp_lt_f32_e32 vcc, s96, v1
	s_cbranch_vccnz .Lq_re_on

; __device__ __forceinline__ void diff_unit_lds(LAS unsigned char* lds, const bf16* Qd, const bf16* Kd, const bf16* VdT, bf16* MIX, const float* ghead, float lam, int head, int u, int wave, int lane) {
;     ...
;             for (int ds = 0; ds < 4; ++ds) S0 = MFMA32(*(const LAS bf16x8*)(st + koff + (((2 * ds + h) ^ kx) << 4)), qf[ds], S0);
;             if (!part) {
; #pragma unroll
;                 for (int ds = 0; ds < 4; ++ds) S1 = MFMA32(*(const LAS bf16x8*)(st + koff + 4096 + (((2 * ds + h) ^ kx) << 4)), qf[ds], S1);
;             }
;             float tmax = S0[0];
; #pragma unroll
;             for (int i = 1; i < 16; ++i) tmax = fmaxf(tmax, S0[i]);
;             if (masked) tmax = -1e30f;
;             if (!part) {
; #pragma unroll
;                 for (int i = 0; i < 16; ++i) tmax = fmaxf(tmax, S1[i]);
;             }
;             tmax = fmaxf(tmax, xhalf(tmax, h));
;             if (T == 0 || __any(tmax > 8.0f)) {
;                 const float delta = (T == 0) ? tmax : fmaxf(tmax, 0.f), alpha = (T == 0) ? 1.0f : __builtin_amdgcn_exp2f(-delta);
;                 l *= alpha;
; #pragma unroll
;                 for (int b = 0; b < 4; ++b)
; #pragma unroll
;                     for (int i = 0; i < 16; ++i) O[b][i] *= alpha;
;                 m_used += delta;
; #pragma unroll
;                 for (int i = 0; i < 16; ++i) { NEGM[i] = -m_used; S0[i] -= delta; S1[i] -= delta; }
;             }
;             {
;                 float p[16]; float ps = 0.f;
; #pragma unroll
;                 for (int i = 0; i < 16; ++i) { p[i] = __builtin_amdgcn_exp2f(S0[i]); ps += p[i]; }
;                 if (masked) {
; #pragma unroll
;                     for (int i = 0; i < 16; ++i) p[i] = 0.f;
;                     ps = 0.f;
;                 }
;                 l += ps;
;                 const bf16x8 pk0 = pack8(p[0], p[1], p[2], p[3], p[4], p[5], p[6], p[7]);
;                 const bf16x8 pk1 = pack8(p[8], p[9], p[10], p[11], p[12], p[13], p[14], p[15]);
; #pragma unroll
;                 for (int b = 0; b < 4; ++b) {
;                     const bf16x8 v0 = *(const LAS bf16x8*)(st + voff + b * 4096 + (((2 * h) ^ vx) << 4));
;                     const bf16x8 v1 = *(const LAS bf16x8*)(st + voff + b * 4096 + (((2 * h + 1) ^ vx) << 4));
;                     O[b] = MFMA32(v0, pk0, O[b]); O[b] = MFMA32(v1, pk1, O[b]);
;                 }
;             }
.Lq_wd_on:
	s_barrier
	v_add_u32_e32 v203, s58, v209
	ds_read_b128 v[164:167], v203
	v_add_u32_e32 v204, s58, v210
	ds_read_b128 v[168:171], v204
	v_add_u32_e32 v192, s58, v211
	ds_read_b128 v[172:175], v192
	v_add_u32_e32 v193, s58, v212
	ds_read_b128 v[176:179], v193
	v_mfma_f32_32x32x16_bf16 v[50:65], v[238:241], v[102:105], v[50:65]
	ds_read_b128 v[238:241], v213 offset:16384
	v_exp_f32_e32 v86, v86
	v_add_f32_e32 v251, v251, v84
	v_exp_f32_e32 v87, v87
	v_add_f32_e32 v251, v251, v85
	v_exp_f32_e32 v88, v88
	v_mfma_f32_32x32x16_bf16 v[34:49], v[242:245], v[102:105], v[34:49]
	ds_read_b128 v[242:245], v213 offset:20480
	v_add_f32_e32 v251, v251, v86
	v_exp_f32_e32 v89, v89
	v_add_f32_e32 v251, v251, v87
	v_cvt_pk_bf16_f32 v82, v82, v83
	v_add_f32_e32 v251, v251, v88
	v_mfma_f32_32x32x16_bf16 v[18:33], v[246:249], v[102:105], v[18:33]
	ds_read_b128 v[246:249], v213 offset:24576
	v_cvt_pk_bf16_f32 v83, v84, v85
	v_cvt_pk_bf16_f32 v84, v86, v87
	v_cvt_pk_bf16_f32 v85, v88, v89
	v_add_f32_e32 v251, v251, v89
	v_mfma_f32_32x32x16_bf16 v[2:17], v[252:255], v[102:105], v[2:17]
	ds_read_b128 v[252:255], v213 offset:28672
	v_exp_f32_e32 v90, v90
	v_exp_f32_e32 v91, v91
	v_exp_f32_e32 v92, v92
	v_add_f32_e32 v251, v251, v90
	s_cmp_lg_u32 s59, 0
	s_cbranch_scc1 .Lq_rl_on
.Lq_rlc_on:
	s_waitcnt lgkmcnt(4)
	v_mfma_f32_32x32x16_bf16 v[98:113], v[164:167], v[126:129], v[66:81]
	v_exp_f32_e32 v93, v93
	v_add_f32_e32 v251, v251, v91
	v_exp_f32_e32 v94, v94
	v_add_f32_e32 v251, v251, v92
	v_mfma_f32_32x32x16_bf16 v[98:113], v[168:171], v[122:125], v[98:113]
	v_exp_f32_e32 v95, v95
	v_add_f32_e32 v251, v251, v93
	v_exp_f32_e32 v96, v96
	v_add_f32_e32 v251, v251, v94
	v_mfma_f32_32x32x16_bf16 v[98:113], v[172:175], v[118:121], v[98:113]
	v_exp_f32_e32 v97, v97
	v_add_f32_e32 v251, v251, v95
	v_cvt_pk_bf16_f32 v86, v90, v91
	v_add_f32_e32 v251, v251, v96
	v_mfma_f32_32x32x16_bf16 v[98:113], v[176:179], v[114:117], v[98:113]
	v_cvt_pk_bf16_f32 v87, v92, v93
	v_cvt_pk_bf16_f32 v88, v94, v95
	v_cvt_pk_bf16_f32 v89, v96, v97
	v_add_f32_e32 v251, v251, v97
	v_add_f32_e32 v218, v218, v251
